# seam 0: two-level XCD barrier instead of the cooperative-groups grid sync; P4 preamble max|rpb| with wide loads in flight
# speedup vs baseline: 1.0068x; 1.0068x over previous
.LBB0_119:
	s_cmp_gt_i32 s61, 1
	s_cselect_b64 s[0:1], -1, 0
	s_and_b64 s[8:9], s[8:9], s[0:1]
	s_andn2_b64 vcc, exec, s[8:9]
	s_cbranch_vccnz .LBB0_131
	v_writelane_b32 v254, s71, 10
	v_cndmask_b32_e64 v0, 0, 1, s[4:5]
	s_nop 1
	v_cmp_ne_u32_e64 s[0:1], 1, v0
	s_nop 1
	s_and_b64 vcc, exec, s[0:1]
	s_mov_b64 s[6:7], 0
	s_cbranch_vccnz .Ls0_151
	v_mbcnt_hi_u32_b32 v0, -1, v228
	v_cmp_eq_u32_e32 vcc, 0, v0
	s_and_b64 s[6:7], vcc, exec

.Ls0_203:
	s_or_b64 exec, exec, s[4:5]
	s_waitcnt lgkmcnt(0)
	s_barrier
	v_readlane_b32 s71, v254, 10
	s_cmp_lt_u32 s3, 64
	s_cselect_b64 s[4:5], -1, 0
	s_cmp_gt_i32 s61, 1
	s_cselect_b64 s[0:1], -1, 0

.LBB0_388:
	s_cmp_lt_i32 s60, 5
	s_cselect_b64 s[6:7], -1, 0
	s_add_u32 s26, s30, 0x2c000000
	s_addc_u32 s27, s31, 0
	s_and_b64 s[36:37], s[6:7], s[4:5]
	s_andn2_b64 vcc, exec, s[36:37]
	s_cbranch_vccnz .LBB0_600
	v_mbcnt_hi_u32_b32 v6, -1, v228
	v_mov_b32_e32 v0, v6
	v_mov_b32_e32 v9, 0
	s_waitcnt lgkmcnt(0)
	v_ashrrev_i32_e32 v1, 31, v0
	v_lshlrev_b64 v[2:3], 2, v[0:1]
	v_lshl_add_u64 v[4:5], s[12:13], 0, v[2:3]
	v_lshl_add_u64 v[2:3], s[14:15], 0, v[2:3]
	global_load_dword v8, v[4:5], off
	global_load_dword v7, v[2:3], off
	s_movk_i32 s14, 0xe88
	v_cmp_gt_i32_e32 vcc, s14, v0
	s_and_saveexec_b64 s[6:7], vcc
	v_lshlrev_b32_e32 v1, 4, v0
	s_mov_b64 s[10:11], s[16:17]
	global_load_dwordx4 v[10:13], v1, s[10:11] offset:0
	global_load_dwordx4 v[14:17], v1, s[10:11] offset:1024
	global_load_dwordx4 v[18:21], v1, s[10:11] offset:2048
	global_load_dwordx4 v[22:25], v1, s[10:11] offset:3072
	s_add_u32 s10, s10, 0x1000
	s_addc_u32 s11, s11, 0
	global_load_dwordx4 v[26:29], v1, s[10:11] offset:0
	global_load_dwordx4 v[30:33], v1, s[10:11] offset:1024
	global_load_dwordx4 v[34:37], v1, s[10:11] offset:2048
	global_load_dwordx4 v[38:41], v1, s[10:11] offset:3072
	s_add_u32 s10, s10, 0x1000
	s_addc_u32 s11, s11, 0
	global_load_dwordx4 v[42:45], v1, s[10:11] offset:0
	global_load_dwordx4 v[46:49], v1, s[10:11] offset:1024
	global_load_dwordx4 v[50:53], v1, s[10:11] offset:2048
	global_load_dwordx4 v[54:57], v1, s[10:11] offset:3072
	s_add_u32 s10, s10, 0x1000
	s_addc_u32 s11, s11, 0
	global_load_dwordx4 v[58:61], v1, s[10:11] offset:0
	global_load_dwordx4 v[62:65], v1, s[10:11] offset:1024
	v_mov_b32_e32 v66, 0
	v_mov_b32_e32 v67, 0
	v_mov_b32_e32 v68, 0
	v_mov_b32_e32 v69, 0
	v_cmp_gt_u32_e32 vcc, 34, v0
	s_and_saveexec_b64 s[8:9], vcc
	global_load_dwordx4 v[66:69], v1, s[10:11] offset:2048
	s_or_b64 exec, exec, s[8:9]
	s_waitcnt vmcnt(0)
	v_max_f32_e64 v9, |v10|, |v11|
	v_max3_f32 v9, v9, |v12|, |v13|
	v_max3_f32 v9, v9, |v14|, |v15|
	v_max3_f32 v9, v9, |v16|, |v17|
	v_max3_f32 v9, v9, |v18|, |v19|
	v_max3_f32 v9, v9, |v20|, |v21|
	v_max3_f32 v9, v9, |v22|, |v23|
	v_max3_f32 v9, v9, |v24|, |v25|
	v_max3_f32 v9, v9, |v26|, |v27|
	v_max3_f32 v9, v9, |v28|, |v29|
	v_max3_f32 v9, v9, |v30|, |v31|
	v_max3_f32 v9, v9, |v32|, |v33|
	v_max3_f32 v9, v9, |v34|, |v35|
	v_max3_f32 v9, v9, |v36|, |v37|
	v_max3_f32 v9, v9, |v38|, |v39|
	v_max3_f32 v9, v9, |v40|, |v41|
	v_max3_f32 v9, v9, |v42|, |v43|
	v_max3_f32 v9, v9, |v44|, |v45|
	v_max3_f32 v9, v9, |v46|, |v47|
	v_max3_f32 v9, v9, |v48|, |v49|
	v_max3_f32 v9, v9, |v50|, |v51|
	v_max3_f32 v9, v9, |v52|, |v53|
	v_max3_f32 v9, v9, |v54|, |v55|
	v_max3_f32 v9, v9, |v56|, |v57|
	v_max3_f32 v9, v9, |v58|, |v59|
	v_max3_f32 v9, v9, |v60|, |v61|
	v_max3_f32 v9, v9, |v62|, |v63|
	v_max3_f32 v9, v9, |v64|, |v65|
	v_max3_f32 v9, v9, |v66|, |v67|
	v_max3_f32 v9, v9, |v68|, |v69|
